# prep1: pre-check global maxima before atomicMax (skips contended atomics); plus LDS-DMA K/V staging in attention A and C
# speedup vs baseline: 1.0206x; 1.0206x over previous
.LBB0_550:
	v_and_b32_e32 v0, 15, v199
	v_cmp_eq_u32_e32 vcc, 0, v0
	s_and_saveexec_b64 s[4:5], vcc
	s_cbranch_execz .LBB0_553
	v_lshrrev_b32_e32 v0, 1, v162
	v_readlane_b32 s6, v252, 48
	v_cmp_gt_u32_e32 vcc, 32, v162
	s_nop 0
	v_lshl_or_b32 v0, s6, 6, v0
	s_waitcnt vmcnt(0) lgkmcnt(0)
	v_lshl_add_u64 v[2:3], v[160:161], 0, v[0:1]
	global_load_dword v4, v[2:3], off offset:256 sc0 sc1
	global_load_dword v5, v[2:3], off offset:260 sc0 sc1
	global_load_dword v6, v[2:3], off offset:288 sc0 sc1
	global_load_dword v7, v[2:3], off offset:292 sc0 sc1
	s_waitcnt vmcnt(0)
	s_mov_b64 s[8:9], exec
	v_cmp_gt_u32_e64 s[12:13], v38, v4
	s_nop 1
	s_mov_b64 exec, s[12:13]
	flat_atomic_umax v[2:3], v38 offset:256
	s_mov_b64 exec, s[8:9]
	v_cmp_gt_u32_e64 s[12:13], v40, v5
	s_nop 1
	s_mov_b64 exec, s[12:13]
	flat_atomic_umax v[2:3], v40 offset:260
	s_mov_b64 exec, s[8:9]
	v_cmp_gt_u32_e64 s[12:13], v37, v6
	s_nop 1
	s_and_b64 exec, s[12:13], vcc
	flat_atomic_umax v[2:3], v37 offset:288
	s_mov_b64 exec, s[8:9]
	v_cmp_gt_u32_e64 s[12:13], v39, v7
	s_nop 1
	s_and_b64 exec, s[12:13], vcc
	flat_atomic_umax v[2:3], v39 offset:292
